# scan: removed 5 spurious vmcnt waits around prefetch of next chunk rows
# speedup vs baseline: 1.0115x; 1.0115x over previous
; __device__ __forceinline__ void scan_phase(PREF p, char* smem, const int wid_u) {
;     ...
;       if (c + 2 < nch) {
;         const int is2 = (c + 2) * 32 + th * 16 + tl;
;         const int t2 = d ? T - 1 - is2 : is2;
;         const int row2 = r0seq + t2;
;         if (role >= 2) load_raw16(ra, z, row2, t2, T, colA);
;         if (role == 3) load_raw16(rb, z, row2, t2, T, colB);
;         if (role < 2) {
;           const int is3 = (c + 2) * 32 + th * 16 + fr, t3 = d ? T - 1 - is3 : is3;
;           const bf16_t* ap = P_ALORA + (unsigned)((r0seq + t3) * 256 + alo);
;           ra.c0 = *(const uint4*)ap; ra.c1 = *(const uint4*)(ap + 32);
;         }
.LBB0_586:
	v_add_u32_e32 v13, s47, v169
	v_add3_u32 v12, v77, s93, 64
	v_add_u32_e32 v13, 0xffffffbf, v13
	v_cndmask_b32_e64 v12, v13, v12, s[2:3]
	v_add_u32_e32 v12, s91, v12
	v_lshl_or_b32 v78, v12, 8, v114
	v_lshl_add_u64 v[16:17], v[78:79], 1, s[74:75]
	global_load_dwordx4 v[12:15], v[16:17], off
	s_nop 0
	global_load_dwordx4 v[16:19], v[16:17], off offset:64

; __device__ __forceinline__ void load_raw16(Raw16& r, const bf16_t* __restrict__ z, int row, int t, int T, int col) {
;   const bf16_t* pz = z + (unsigned)(row * ZLD + col);
;   r.c0 = *(const uint4*)pz; r.c1 = *(const uint4*)(pz + 8);
;   r.p0 = make_uint4(0, 0, 0, 0); r.p1 = r.p0; r.n0 = r.p0; r.n1 = r.p0;
;   if (t > 0) { r.p0 = *(const uint4*)(pz - ZLD); r.p1 = *(const uint4*)(pz - ZLD + 8); }
;   if (t < T - 1) { r.n0 = *(const uint4*)(pz + ZLD); r.n1 = *(const uint4*)(pz + ZLD + 8); }
.LBB0_592:
	v_mad_u64_u32 v[0:1], s[82:83], v59, s88, v[74:75]
	v_mov_b32_e32 v1, v79
	v_lshl_add_u64 v[56:57], v[0:1], 1, s[50:51]
	global_load_dwordx4 v[16:19], v[56:57], off offset:16
	global_load_dwordx4 v[12:15], v[56:57], off
	v_mov_b32_e32 v2, v79
	v_mov_b32_e32 v3, v79
	v_mov_b32_e32 v0, 0
	v_mov_b64_e32 v[10:11], v[2:3]
	v_mov_b64_e32 v[6:7], v[2:3]
	v_mov_b64_e32 v[8:9], v[0:1]
	v_mov_b64_e32 v[4:5], v[0:1]
	s_and_saveexec_b64 s[82:83], s[40:41]
	s_cbranch_execz .LBB0_594
	v_add_co_u32_e32 v4, vcc, 0xfffff000, v56
	v_lshl_add_u64 v[8:9], v[56:57], 0, s[76:77]
	s_nop 0
	v_addc_co_u32_e32 v5, vcc, -1, v57, vcc
	global_load_dwordx4 v[4:7], v[4:5], off offset:-1024
	s_nop 0
	global_load_dwordx4 v[8:11], v[8:9], off offset:16

; __device__ __forceinline__ void load_raw16(Raw16& r, const bf16_t* __restrict__ z, int row, int t, int T, int col) {
;   const bf16_t* pz = z + (unsigned)(row * ZLD + col);
;   r.c0 = *(const uint4*)pz; r.c1 = *(const uint4*)(pz + 8);
;   r.p0 = make_uint4(0, 0, 0, 0); r.p1 = r.p0; r.n0 = r.p0; r.n1 = r.p0;
;   if (t > 0) { r.p0 = *(const uint4*)(pz - ZLD); r.p1 = *(const uint4*)(pz - ZLD + 8); }
;   if (t < T - 1) { r.n0 = *(const uint4*)(pz + ZLD); r.n1 = *(const uint4*)(pz + ZLD + 8); }
.LBB0_597:
	v_mad_u64_u32 v[20:21], s[40:41], v59, s88, v[76:77]
	v_mov_b32_e32 v21, v79
	v_lshl_add_u64 v[56:57], v[20:21], 1, s[50:51]
	global_load_dwordx4 v[20:23], v[56:57], off offset:16
	global_load_dwordx4 v[24:27], v[56:57], off
	v_mov_b32_e32 v34, v79
	v_mov_b32_e32 v35, v79
	v_mov_b32_e32 v32, 0
	v_mov_b32_e32 v33, v79
	v_mov_b64_e32 v[42:43], v[34:35]
	v_mov_b64_e32 v[38:39], v[34:35]
	v_cmp_lt_i32_e32 vcc, 0, v58
	v_mov_b64_e32 v[40:41], v[32:33]
	v_mov_b64_e32 v[36:37], v[32:33]
	s_and_saveexec_b64 s[40:41], vcc
	s_cbranch_execz .LBB0_599
	v_add_co_u32_e32 v36, vcc, 0xfffff000, v56
	v_lshl_add_u64 v[40:41], v[56:57], 0, s[76:77]
	s_nop 0
	v_addc_co_u32_e32 v37, vcc, -1, v57, vcc
	global_load_dwordx4 v[36:39], v[36:37], off offset:-1024
	s_nop 0
	global_load_dwordx4 v[40:43], v[40:41], off offset:16
